# work-queue dequeue atomic issued before the unit epilogue stores (fox) / after the slc epilogue's up-front PART loads, counted vmcnt at the loop head; plus window PART RMW and slc epilogue loads de-se
# speedup vs baseline: 1.0045x; 1.0009x over previous
; DI int transposes_total(bool late) { int total = 0; for (int s = 0; s < NSEG; ++s) if (seg_late(s) == late) total += (SEGS[s].K / 64) * ((SEGS[s].len + 31) / 32); return total; }
; __global__ void __launch_bounds__(512) fwd_kernel(Params P) {
;     ...
;         for (;;) {
;             __syncthreads();
;             if (tid == 0) qs_[0] = (int)atomicAdd(CTL + CW_Q3 + REPQ, 1u);
;             __syncthreads();
;             const int u = qs_[0];
;             const int nlate = transposes_total(true), nlate_wg = (nlate + 7) >> 3;
;             if (u >= 128 + 2048 + nlate_wg) break;
.LBB0_462:
	v_readlane_b32 s0, v251, 15
	v_readlane_b32 s1, v251, 16
	s_cmp_lt_i32 s0, 4
	v_readlane_b32 s2, v251, 17
	v_readlane_b32 s3, v251, 18
	s_cselect_b64 s[0:1], -1, 0
	s_and_b64 s[2:3], s[0:1], s[4:5]
	s_andn2_b64 vcc, exec, s[2:3]
	s_cbranch_vccnz .LBB0_820
	v_writelane_b32 v251, s2, 41
	s_getpc_b64 s[0:1]
	s_add_u32 s0, s0, SEGS@rel32@lo+544
	s_addc_u32 s1, s1, SEGS@rel32@hi+552
	v_writelane_b32 v251, s3, 42
	s_getpc_b64 s[2:3]
	s_add_u32 s2, s2, SEGS@rel32@lo+552
	s_addc_u32 s3, s3, SEGS@rel32@hi+560
	s_getpc_b64 s[4:5]
	s_add_u32 s4, s4, SEGS@rel32@lo+592
	s_addc_u32 s5, s5, SEGS@rel32@hi+600
	s_getpc_b64 s[6:7]
	s_add_u32 s6, s6, SEGS@rel32@lo+600
	s_addc_u32 s7, s7, SEGS@rel32@hi+608
	s_getpc_b64 s[8:9]
	s_add_u32 s8, s8, SEGS@rel32@lo+640
	s_addc_u32 s9, s9, SEGS@rel32@hi+648
	s_getpc_b64 s[10:11]
	s_add_u32 s10, s10, SEGS@rel32@lo+648
	s_addc_u32 s11, s11, SEGS@rel32@hi+656
	s_getpc_b64 s[12:13]
	s_add_u32 s12, s12, SEGS@rel32@lo+688
	s_addc_u32 s13, s13, SEGS@rel32@hi+696
	s_getpc_b64 s[14:15]
	s_add_u32 s14, s14, SEGS@rel32@lo+696
	s_addc_u32 s15, s15, SEGS@rel32@hi+704
	s_load_dword s0, s[0:1], 0x0
	s_nop 0
	s_load_dword s16, s[2:3], 0x0
	s_load_dword s1, s[4:5], 0x0
	s_nop 0
	s_load_dword s6, s[6:7], 0x0
	s_nop 0
	s_load_dword s2, s[8:9], 0x0
	s_load_dword s7, s[10:11], 0x0
	s_load_dword s3, s[12:13], 0x0
	s_nop 0
	s_load_dword s8, s[14:15], 0x0
	s_waitcnt lgkmcnt(0)
	s_ashr_i32 s4, s0, 31
	s_lshr_b32 s4, s4, 26
	s_add_i32 s0, s0, s4
	s_add_i32 s4, s16, 31
	s_ashr_i32 s5, s4, 31
	s_lshr_b32 s5, s5, 27
	s_add_i32 s4, s4, s5
	s_ashr_i32 s0, s0, 6
	s_ashr_i32 s4, s4, 5
	s_mul_i32 s64, s4, s0
	s_ashr_i32 s0, s1, 31
	s_lshr_b32 s0, s0, 26
	s_add_i32 s1, s1, s0
	s_ashr_i32 s0, s1, 6
	s_add_i32 s1, s6, 31
	s_ashr_i32 s4, s1, 31
	s_lshr_b32 s4, s4, 27
	s_add_i32 s1, s1, s4
	s_ashr_i32 s1, s1, 5
	s_mul_i32 s65, s1, s0
	s_ashr_i32 s1, s2, 31
	s_lshr_b32 s1, s1, 26
	s_add_i32 s2, s2, s1
	s_ashr_i32 s1, s2, 6
	s_add_i32 s2, s7, 31
	s_ashr_i32 s4, s2, 31
	s_lshr_b32 s4, s4, 27
	s_add_i32 s2, s2, s4
	s_ashr_i32 s2, s2, 5
	s_mul_i32 s74, s2, s1
	s_ashr_i32 s1, s3, 31
	s_lshr_b32 s1, s1, 26
	s_add_i32 s3, s3, s1
	s_add_i32 s2, s8, 31
	s_ashr_i32 s1, s3, 6
	s_ashr_i32 s3, s2, 31
	s_lshr_b32 s3, s3, 27
	s_add_i32 s2, s2, s3
	v_writelane_b32 v251, s96, 43
	s_add_i32 s0, s65, s64
	s_ashr_i32 s2, s2, 5
	v_writelane_b32 v251, s97, 44
	s_add_i32 s0, s0, s74
	s_mul_i32 s75, s2, s1
	v_writelane_b32 v251, s16, 45
	s_add_i32 s16, s0, s75
	s_getpc_b64 s[0:1]
	s_add_u32 s0, s0, SEGS@rel32@lo+736
	s_addc_u32 s1, s1, SEGS@rel32@hi+744
	s_getpc_b64 s[2:3]
	s_add_u32 s2, s2, SEGS@rel32@lo+744
	s_addc_u32 s3, s3, SEGS@rel32@hi+752
	v_writelane_b32 v251, s6, 46
	s_getpc_b64 s[4:5]
	s_add_u32 s4, s4, SEGS@rel32@lo+880
	s_addc_u32 s5, s5, SEGS@rel32@hi+888
	v_writelane_b32 v251, s7, 47
	s_getpc_b64 s[6:7]
	s_add_u32 s6, s6, SEGS@rel32@lo+888
	s_addc_u32 s7, s7, SEGS@rel32@hi+896
	v_writelane_b32 v251, s8, 48
	s_getpc_b64 s[8:9]
	s_add_u32 s8, s8, SEGS@rel32@lo+928
	s_addc_u32 s9, s9, SEGS@rel32@hi+936
	s_getpc_b64 s[10:11]
	s_add_u32 s10, s10, SEGS@rel32@lo+936
	s_addc_u32 s11, s11, SEGS@rel32@hi+944
	s_getpc_b64 s[12:13]
	s_add_u32 s12, s12, SEGS@rel32@lo+976
	s_addc_u32 s13, s13, SEGS@rel32@hi+984
	s_getpc_b64 s[14:15]
	s_add_u32 s14, s14, SEGS@rel32@lo+984
	s_addc_u32 s15, s15, SEGS@rel32@hi+992
	s_load_dword s0, s[0:1], 0x0
	s_nop 0
	s_load_dword s17, s[2:3], 0x0
	s_load_dword s1, s[4:5], 0x0
	s_nop 0
	s_load_dword s6, s[6:7], 0x0
	s_nop 0
	s_load_dword s2, s[8:9], 0x0
	s_load_dword s7, s[10:11], 0x0
	s_load_dword s3, s[12:13], 0x0
	s_nop 0
	s_load_dword s8, s[14:15], 0x0
	s_waitcnt lgkmcnt(0)
	s_ashr_i32 s4, s0, 31
	s_lshr_b32 s4, s4, 26
	s_add_i32 s0, s0, s4
	s_add_i32 s4, s17, 31
	s_ashr_i32 s5, s4, 31
	s_lshr_b32 s5, s5, 27
	s_add_i32 s4, s4, s5
	s_ashr_i32 s0, s0, 6
	s_ashr_i32 s4, s4, 5
	s_mul_i32 s81, s4, s0
	s_ashr_i32 s4, s1, 31
	s_lshr_b32 s4, s4, 26
	s_add_i32 s1, s1, s4
	s_add_i32 s4, s6, 31
	s_ashr_i32 s5, s4, 31
	s_lshr_b32 s5, s5, 27
	s_add_i32 s4, s4, s5
	s_ashr_i32 s1, s1, 6
	s_ashr_i32 s4, s4, 5
	s_mul_i32 s91, s4, s1
	s_ashr_i32 s1, s2, 31
	s_lshr_b32 s1, s1, 26
	s_add_i32 s2, s2, s1
	s_ashr_i32 s1, s2, 6
	s_add_i32 s2, s7, 31
	s_ashr_i32 s4, s2, 31
	s_lshr_b32 s4, s4, 27
	s_add_i32 s2, s2, s4
	s_ashr_i32 s2, s2, 5
	s_mul_i32 s92, s2, s1
	s_ashr_i32 s1, s3, 31
	s_lshr_b32 s1, s1, 26
	s_add_i32 s3, s3, s1
	s_add_i32 s2, s8, 31
	s_ashr_i32 s1, s3, 6
	s_ashr_i32 s3, s2, 31
	s_lshr_b32 s3, s3, 27
	s_add_i32 s0, s16, s81
	s_add_i32 s2, s2, s3
	s_add_i32 s0, s0, s91
	s_ashr_i32 s2, s2, 5
	s_add_i32 s0, s0, s92
	s_mul_i32 s87, s2, s1
	s_add_i32 s12, s0, s87
	s_getpc_b64 s[0:1]
	s_add_u32 s0, s0, SEGS@rel32@lo+1024
	s_addc_u32 s1, s1, SEGS@rel32@hi+1032
	v_writelane_b32 v251, s17, 49
	s_getpc_b64 s[2:3]
	s_add_u32 s2, s2, SEGS@rel32@lo+1032
	s_addc_u32 s3, s3, SEGS@rel32@hi+1040
	v_writelane_b32 v251, s6, 50
	s_getpc_b64 s[4:5]
	s_add_u32 s4, s4, SEGS@rel32@lo+1072
	s_addc_u32 s5, s5, SEGS@rel32@hi+1080
	v_writelane_b32 v251, s7, 51
	s_getpc_b64 s[6:7]
	s_add_u32 s6, s6, SEGS@rel32@lo+1080
	s_addc_u32 s7, s7, SEGS@rel32@hi+1088
	v_writelane_b32 v251, s8, 52
	s_getpc_b64 s[8:9]
	s_add_u32 s8, s8, SEGS@rel32@lo+1120
	s_addc_u32 s9, s9, SEGS@rel32@hi+1128
	s_getpc_b64 s[10:11]
	s_add_u32 s10, s10, SEGS@rel32@lo+1128
	s_addc_u32 s11, s11, SEGS@rel32@hi+1136
	s_load_dword s0, s[0:1], 0x0
	s_nop 0
	s_load_dword s13, s[2:3], 0x0
	s_load_dword s1, s[4:5], 0x0
	s_nop 0
	s_load_dword s5, s[6:7], 0x0
	s_load_dword s2, s[8:9], 0x0
	s_nop 0
	s_load_dword s6, s[10:11], 0x0
	s_waitcnt lgkmcnt(0)
; DI int transposes_total(bool late) { int total = 0; for (int s = 0; s < NSEG; ++s) if (seg_late(s) == late) total += (SEGS[s].K / 64) * ((SEGS[s].len + 31) / 32); return total; }
; DI void qk_acc(lptr Kt, const bf16x8 (&qf)[4], f32x16& s0, f32x16& s1, int lane) {
;     const int i = lane & 31, hi = lane >> 5;
;     const int krow = (i & 19) | ((i & 4) << 1) | ((i & 8) >> 1);
;     lptr kp = Kt + krow * KPB + hi * 16;
; __global__ void __launch_bounds__(512) fwd_kernel(Params P) {
;     ...
;         for (;;) {
;             __syncthreads();
;             if (tid == 0) qs_[0] = (int)atomicAdd(CTL + CW_Q3 + REPQ, 1u);
;             __syncthreads();
;             const int u = qs_[0];
;             const int nlate = transposes_total(true), nlate_wg = (nlate + 7) >> 3;
;             if (u >= 128 + 2048 + nlate_wg) break;
	s_ashr_i32 s3, s0, 31
	s_lshr_b32 s3, s3, 26
	s_add_i32 s0, s0, s3
	s_add_i32 s3, s13, 31
	s_ashr_i32 s4, s3, 31
	s_lshr_b32 s4, s4, 27
	s_add_i32 s3, s3, s4
	s_ashr_i32 s0, s0, 6
	s_ashr_i32 s3, s3, 5
	s_mul_i32 s88, s3, s0
	s_ashr_i32 s3, s1, 31
	s_lshr_b32 s3, s3, 26
	s_add_i32 s1, s1, s3
	s_add_i32 s3, s5, 31
	s_ashr_i32 s4, s3, 31
	s_lshr_b32 s4, s4, 27
	s_add_i32 s3, s3, s4
	s_ashr_i32 s1, s1, 6
	s_ashr_i32 s3, s3, 5
	s_mul_i32 s89, s3, s1
	s_ashr_i32 s1, s2, 31
	s_lshr_b32 s1, s1, 26
	s_add_i32 s2, s2, s1
	s_ashr_i32 s1, s2, 6
	s_add_i32 s2, s6, 31
	s_ashr_i32 s3, s2, 31
	s_lshr_b32 s3, s3, 27
	s_add_i32 s2, s2, s3
	v_writelane_b32 v251, s13, 53
	s_add_i32 s0, s12, s88
	s_ashr_i32 s2, s2, 5
	v_writelane_b32 v251, s5, 54
	s_add_i32 s0, s0, s89
	s_mul_i32 s2, s2, s1
	v_writelane_b32 v251, s6, 55
	s_add_i32 s0, s0, s2
	v_writelane_b32 v251, s0, 56
	s_add_i32 s0, s0, 7
	s_ashr_i32 s0, s0, 3
	s_addk_i32 s0, 0x880
	v_writelane_b32 v251, s0, 57
	s_add_u32 s0, s34, 0x7800000
	s_addc_u32 s1, s35, 0
	v_writelane_b32 v251, s0, 58
	v_lshrrev_b32_e32 v3, 3, v194
	v_lshlrev_b32_e32 v0, 3, v194
	v_writelane_b32 v251, s1, 59
	s_add_u32 s0, s34, 0xfd00000
	v_writelane_b32 v251, s0, 60
	s_addc_u32 s0, s35, 0
	v_writelane_b32 v251, s0, 61
	s_add_u32 s0, s34, 0x3100000
	v_writelane_b32 v251, s0, 62
	s_addc_u32 s0, s35, 0
	s_lshl_b32 s1, s90, 5
	s_add_u32 s2, s34, 0x3210000
	s_addc_u32 s3, s35, 0
	s_add_u32 s4, s34, 0x3300000
	v_lshlrev_b32_e32 v4, 4, v194
	s_addc_u32 s5, s35, 0
	v_and_b32_e32 v130, 56, v0
	v_mul_u32_u24_e32 v0, 0x90, v3
	v_and_b32_e32 v4, 0x70, v4
	s_add_u32 s6, s34, 0x14200000
	v_add3_u32 v127, 0, v0, v4
	v_lshlrev_b32_e32 v4, 1, v194
	v_lshrrev_b32_e32 v5, 1, v192
	s_addc_u32 s7, s35, 0
	v_and_b32_e32 v0, 19, v194
	v_and_b32_e32 v4, 8, v4
	v_and_b32_e32 v6, 4, v5
	v_writelane_b32 v250, s6, 0
	v_writelane_b32 v251, s0, 63
	v_or3_b32 v0, v4, v0, v6
	v_writelane_b32 v250, s7, 1
	s_bfe_u32 s0, s30, 0x20006
	v_mov_b32_e32 v1, 0
	v_mul_u32_u24_e32 v131, 0x90, v0
	v_writelane_b32 v250, s0, 2
	v_lshlrev_b32_e32 v0, 7, v3
	v_and_b32_e32 v122, 31, v194
	v_and_b32_e32 v133, 16, v5
	s_lshl_b32 s0, s90, 3
	v_writelane_b32 v250, s2, 3
	v_lshlrev_b32_e32 v6, 1, v130
	v_mov_b32_e32 v7, v1
	v_lshl_add_u64 v[4:5], s[2:3], 0, v[0:1]
	v_mul_u32_u24_e32 v128, 0x840, v3
	v_mul_u32_u24_e32 v132, 0x4040, v3
	s_mov_b32 s93, s0
	s_and_b32 s7, s0, 0x1fffffe0
	v_lshl_add_u64 v[136:137], v[4:5], 0, v[6:7]
	v_lshlrev_b32_e32 v4, 11, v3
	s_add_i32 s0, 0, 0x1a544
	v_lshlrev_b32_e32 v3, 2, v122
	v_writelane_b32 v250, s3, 4
	v_add_u32_e32 v171, s0, v3
	s_add_i32 s0, 0, 0x19904
	v_writelane_b32 v250, s4, 5
	s_add_u32 s2, s34, 0x3200000
	s_addc_u32 s3, s35, 0
	v_writelane_b32 v250, s5, 6
	v_lshlrev_b32_e32 v10, 2, v194
	v_or_b32_e32 v179, s7, v122
	v_writelane_b32 v250, s2, 7
	v_add_u32_e32 v180, s0, v10
	v_lshl_add_u32 v186, v179, 5, s0
	v_writelane_b32 v250, s3, 8
	s_add_i32 s0, s90, 0xffffbc00
	v_writelane_b32 v250, s0, 9
	s_mul_i32 s0, s90, 0x2100
	v_readlane_b32 s8, v251, 4
	v_mov_b32_e32 v5, v1
	s_add_i32 s0, s0, 0
	v_readlane_b32 s10, v251, 6
	v_readlane_b32 s11, v251, 7
	v_lshrrev_b32_e32 v124, 5, v192
	v_lshl_add_u64 v[8:9], s[4:5], 0, v[4:5]
	s_movk_i32 s6, 0x104
	v_mov_b32_e32 v5, 0x8200
	s_cmp_lg_u64 s[10:11], 0
	v_lshlrev_b32_e32 v126, 3, v124
	v_lshl_add_u64 v[138:139], v[8:9], 0, v[6:7]
	v_lshlrev_b64 v[6:7], v192, -1
	v_mad_u32_u24 v177, v192, s6, v5
	v_and_b32_e32 v5, 7, v194
	s_cselect_b64 s[2:3], -1, 0
	v_or_b32_e32 v9, s1, v122
	v_not_b32_e32 v140, v6
	v_lshlrev_b32_e64 v6, v194, -1
	v_writelane_b32 v250, s2, 10
	v_lshrrev_b32_e32 v188, 3, v192
	v_sub_u32_e32 v195, v9, v126
	v_lshlrev_b32_e32 v9, 4, v5
	v_lshl_add_u32 v181, v5, 2, 0
	v_not_b32_e32 v185, v6
	v_writelane_b32 v250, s3, 11
	v_mul_u32_u24_e32 v6, 0x84, v130
	v_lshlrev_b32_e32 v8, 2, v188
	v_or_b32_e32 v4, v4, v9
	v_mov_b32_e32 v5, v1
	v_add_u32_e32 v3, s0, v3
	v_add3_u32 v189, s0, v6, v8
	v_writelane_b32 v250, s1, 12
; __global__ void __launch_bounds__(512) fwd_kernel(Params P) {
;     ...
;         for (;;) {
;             __syncthreads();
;             if (tid == 0) qs_[0] = (int)atomicAdd(CTL + CW_Q3 + REPQ, 1u);
;             __syncthreads();
;             const int u = qs_[0];
	v_lshl_add_u64 v[4:5], s[34:35], 0, v[4:5]
	s_mov_b64 s[0:1], 0x3300080
	v_or_b32_e32 v0, v0, v9
	v_lshl_add_u64 v[142:143], v[4:5], 0, s[0:1]
	v_lshl_add_u64 v[4:5], s[34:35], 0, v[0:1]
	s_mov_b64 s[0:1], 0x3212000
	v_lshl_add_u64 v[144:145], v[4:5], 0, s[0:1]
	s_movk_i32 s0, 0x100
	v_writelane_b32 v250, s7, 13
	v_cmp_gt_u32_e64 s[0:1], s0, v194
	s_cmp_eq_u64 s[38:39], 0
	v_sub_u32_e32 v0, v126, v122
	v_writelane_b32 v250, s0, 14
	v_readlane_b32 s14, v251, 10
	v_readlane_b32 s15, v251, 11
	v_writelane_b32 v250, s1, 15
	s_cselect_b64 s[0:1], -1, 0
	v_writelane_b32 v250, s0, 16
	v_subrev_u32_e32 v201, s7, v0
	v_lshlrev_b32_e32 v0, 2, v192
	v_writelane_b32 v250, s1, 17
	s_add_i32 s0, 0, 0x9200
	v_writelane_b32 v250, s0, 18
	v_cmp_gt_u32_e64 s[0:1], 64, v194
	v_lshlrev_b32_e32 v2, 6, v194
	v_add_u32_e32 v129, 0, v10
	v_writelane_b32 v250, s0, 19
	v_mul_u32_u24_e32 v135, 0x90, v122
	v_not_b32_e32 v123, v7
	v_writelane_b32 v250, s1, 20
	v_cmp_lt_u32_e64 s[0:1], 31, v192
	v_lshrrev_b32_e32 v182, 5, v194
	v_readlane_b32 s9, v251, 5
	v_writelane_b32 v250, s0, 21
	v_readlane_b32 s12, v251, 8
	v_readlane_b32 s13, v251, 9
	v_writelane_b32 v250, s1, 22
	v_cmp_ne_u32_e64 s[0:1], 0, v192
	v_mul_u32_u24_e32 v7, 0x84, v124
	v_or_b32_e32 v6, 0x3c0, v194
	v_writelane_b32 v250, s0, 23
	v_or_b32_e32 v8, 0x7c0, v194
	v_or_b32_e32 v10, 0xbc0, v194
	v_writelane_b32 v250, s1, 24
	v_cmp_gt_u32_e64 s[0:1], 16, v194
	v_or_b32_e32 v12, 0xfc0, v194
	v_lshl_add_u64 v[146:147], s[34:35], 0, v[0:1]
	v_writelane_b32 v250, s0, 25
	s_mov_b32 s18, 0x41b00000
	s_mov_b32 s4, 0x42580000
	v_writelane_b32 v250, s1, 26
	v_cmp_lt_u32_e64 s[0:1], 31, v194
	s_mov_b32 s14, 0x42500000
	s_mov_b32 s16, 0x42480000
	v_writelane_b32 v250, s0, 27
	s_mov_b32 s94, 0x42400000
	s_mov_b32 s96, 0x42180000
	v_writelane_b32 v250, s1, 28
	s_mov_b64 s[0:1], 0
	v_writelane_b32 v250, s0, 29
	s_mov_b32 s84, 0x42100000
	s_mov_b32 s72, 0x42080000
	v_writelane_b32 v250, s1, 30
	v_writelane_b32 v250, s87, 31
	s_mov_b32 s44, 0x42000000
	v_mbcnt_lo_u32_b32 v0, -1, 0
	v_writelane_b32 v250, s88, 32
	v_lshlrev_b32_e32 v141, 4, v124
	v_lshlrev_b32_e32 v134, 2, v124
	v_add3_u32 v170, 0, v131, v133
	v_add3_u32 v172, 0, v135, v133
	v_lshlrev_b32_e32 v173, 8, v124
	v_mul_u32_u24_e32 v174, 0x104, v192
	v_or_b32_e32 v175, 64, v192
	v_or_b32_e32 v176, 0x80, v192
	v_or_b32_e32 v178, 0xc0, v192
	v_lshl_add_u32 v183, v182, 2, 0
	v_lshlrev_b32_e64 v184, v194, 1
	v_lshlrev_b32_e32 v187, 10, v192
	v_or_b32_e32 v190, 8, v188
	v_or_b32_e32 v191, 16, v188
	v_or_b32_e32 v193, 24, v188
	v_mov_b32_e32 v125, v1
	v_sub_u32_e32 v196, 0, v126
	v_lshl_or_b32 v197, v124, 7, 31
	v_add_u32_e32 v198, 0x9400, v129
	v_add_u32_e32 v199, 0xfffffe00, v194
	v_sub_u32_e32 v200, v179, v126
	v_mov_b32_e32 v202, 0x260
	v_lshlrev_b32_e32 v203, 2, v2
	s_mov_b32 s19, 0x41b80000
	s_mov_b32 s5, 0x425c0000
	s_mov_b32 s15, 0x42540000
	s_mov_b32 s17, 0x424c0000
	s_mov_b32 s95, 0x42440000
	s_mov_b32 s97, 0x421c0000
	s_mov_b32 s85, 0x42140000
	s_mov_b32 s73, 0x420c0000
	s_mov_b32 s45, 0x42040000
	v_lshlrev_b32_e32 v148, 2, v192
	v_lshlrev_b32_e32 v204, 2, v6
	v_lshlrev_b32_e32 v205, 2, v8
	v_lshlrev_b32_e32 v206, 2, v10
	v_lshlrev_b32_e32 v207, 2, v12
	v_mov_b32_e32 v208, 0x1080
	v_mbcnt_hi_u32_b32 v209, -1, v0
	v_mov_b32_e32 v210, 0xf149f2ca
	v_mov_b32_e32 v211, 0x42800000
	v_mov_b32_e32 v212, 0x44
	v_mov_b32_e32 v213, 0x80
	v_add_u32_e32 v214, v3, v7
	s_movk_i32 s10, 0x200
	s_movk_i32 s11, 0x220
	s_movk_i32 s76, 0x21f
	s_movk_i32 s77, 0x23f
	s_mov_b32 s83, 0
	v_cmp_gt_u32_e64 s[8:9], 32, v192
	v_cmp_eq_u32_e64 s[12:13], 0, v192
	s_mov_b32 s80, 0xbfb8aa3b
	v_writelane_b32 v250, s89, 33
	v_writelane_b32 v250, s75, 34
	s_mov_b32 s98, 0
	s_branch .LBB0_468
.Lq_pref:
	s_mov_b32 s98, 0
	s_barrier
	s_mov_b64 s[0:1], exec
	v_readlane_b32 s2, v251, 20
	v_readlane_b32 s3, v251, 21
	s_and_b64 s[2:3], s[0:1], s[2:3]
	s_mov_b64 exec, s[2:3]
	s_cbranch_execz .LBB0_472
	s_waitcnt vmcnt(8)
	ds_write_b32 v1, v249 offset:37632
	s_branch .LBB0_472

; __global__ void __launch_bounds__(512) fwd_kernel(Params P) {
;     ...
;         for (;;) {
;             __syncthreads();
;             if (tid == 0) qs_[0] = (int)atomicAdd(CTL + CW_Q3 + REPQ, 1u);
.LBB0_468:
	s_cmp_lg_u32 s98, 0
	s_cbranch_scc1 .Lq_pref
	s_waitcnt vmcnt(0)
	s_barrier
	s_mov_b64 s[0:1], exec
	v_readlane_b32 s2, v251, 20
	v_readlane_b32 s3, v251, 21
	s_and_b64 s[2:3], s[0:1], s[2:3]
	s_mov_b64 exec, s[2:3]
	s_cbranch_execz .LBB0_472
	s_mov_b64 s[20:21], exec
	v_mbcnt_lo_u32_b32 v0, s20, 0
	v_mbcnt_hi_u32_b32 v0, s21, v0
	v_cmp_eq_u32_e32 vcc, 0, v0
	s_and_saveexec_b64 s[2:3], vcc
	s_cbranch_execz .LBB0_471
	s_bcnt1_i32_b64 s7, s[20:21]
	v_mov_b32_e32 v2, s7
	global_atomic_add v2, v1, v2, s[34:35] sc0

; DI unsigned pk_bf16(float lo, float hi) { f32x2 v = {lo, hi}; bf16x2_t b = __builtin_convertvector(v, bf16x2_t); return __builtin_bit_cast(unsigned, b); }
; DI void store_o_bf16(bf16_t* orow, const f32x16& o0, const f32x16& o1, float sc, int hi) {
; #pragma unroll
;     for (int g4 = 0; g4 < 4; ++g4) {
;         u32x2 w0, w1;
;         w0.x = pk_bf16(o0[4 * g4] * sc, o0[4 * g4 + 1] * sc); w0.y = pk_bf16(o0[4 * g4 + 2] * sc, o0[4 * g4 + 3] * sc);
;         w1.x = pk_bf16(o1[4 * g4] * sc, o1[4 * g4 + 1] * sc); w1.y = pk_bf16(o1[4 * g4 + 2] * sc, o1[4 * g4 + 3] * sc);
;         *(u32x2*)(orow + 8 * g4 + 4 * hi) = w0; *(u32x2*)(orow + 32 + 8 * g4 + 4 * hi) = w1;
;     }
; }
; DI void fox_unit(const Params& P, lptr L, int u, int tid, int lane, int wid) {
;     ...
;     float l = rs.l; l += __shfl_xor(l, 32);
;     const float inv = 1.f / fmaxf(l, 1e-30f);
;     store_o_bf16(ATT + (size_t)(b * SEQ + t) * DM + h * 64, o0, o1, inv, hi);
.LBB0_517:
	s_mov_b64 s[0:1], exec
	v_readlane_b32 s2, v251, 20
	v_readlane_b32 s3, v251, 21
	s_and_b64 s[2:3], s[0:1], s[2:3]
	s_mov_b64 exec, s[2:3]
	s_cbranch_execz .Lq_site0_skip
	v_mov_b32_e32 v249, 1
	global_atomic_add v249, v1, v249, s[34:35] sc0
.Lq_site0_skip:
	s_mov_b64 exec, s[0:1]
	s_mov_b32 s98, 1
	v_and_b32_e32 v3, 64, v209
	v_xor_b32_e32 v2, 32, v209
	v_add_u32_e32 v3, 64, v3
	v_cmp_lt_i32_e32 vcc, v2, v3
	s_lshl_b32 s0, s33, 6
	s_lshl_b32 s82, s0, 1
	v_cndmask_b32_e32 v2, v209, v2, vcc
	v_lshlrev_b32_e32 v2, 2, v2
	ds_bpermute_b32 v2, v2, v159
	s_mov_b64 s[0:1], 0
	s_waitcnt lgkmcnt(0)
	v_add_f32_e32 v2, v159, v2
	v_max_f32_e32 v2, 0xda24260, v2
	v_div_scale_f32 v3, s[2:3], v2, v2, 1.0
	v_rcp_f32_e32 v4, v3
	v_readlane_b32 s2, v251, 39
	v_readlane_b32 s3, v251, 40
	v_fma_f32 v5, -v3, v4, 1.0
	v_fmac_f32_e32 v4, v5, v4
	v_div_scale_f32 v5, vcc, 1.0, v2, 1.0
	v_mul_f32_e32 v6, v5, v4
	v_fma_f32 v7, -v3, v6, v5
	v_fmac_f32_e32 v6, v7, v4
	v_fma_f32 v3, -v3, v6, v5
	v_div_fmas_f32 v3, v3, v4, v6
	v_div_fixup_f32 v2, v3, v2, 1.0
	v_lshlrev_b64 v[4:5], 11, v[0:1]
	v_lshl_add_u64 v[4:5], s[2:3], 0, v[4:5]
	v_pk_mul_f32 v[6:7], v[34:35], v[2:3] op_sel_hi:[1,0]
	v_pk_mul_f32 v[8:9], v[36:37], v[2:3] op_sel_hi:[1,0]
	v_lshl_add_u64 v[4:5], v[4:5], 0, s[82:83]
	v_lshlrev_b32_e32 v0, 1, v134
	v_cvt_pk_bf16_f32 v6, v6, v7
	v_cvt_pk_bf16_f32 v7, v8, v9
	v_pk_mul_f32 v[8:9], v[50:51], v[2:3] op_sel_hi:[1,0]
	v_pk_mul_f32 v[10:11], v[52:53], v[2:3] op_sel_hi:[1,0]
	v_lshl_add_u64 v[4:5], v[4:5], 0, v[0:1]
	v_cvt_pk_bf16_f32 v8, v8, v9
	v_cvt_pk_bf16_f32 v9, v10, v11
	global_store_dwordx2 v[4:5], v[6:7], off
	global_store_dwordx2 v[4:5], v[8:9], off offset:64
	v_pk_mul_f32 v[6:7], v[38:39], v[2:3] op_sel_hi:[1,0]
	v_pk_mul_f32 v[8:9], v[40:41], v[2:3] op_sel_hi:[1,0]
	v_cvt_pk_bf16_f32 v6, v6, v7
	v_cvt_pk_bf16_f32 v7, v8, v9
	v_pk_mul_f32 v[8:9], v[54:55], v[2:3] op_sel_hi:[1,0]
	v_pk_mul_f32 v[10:11], v[56:57], v[2:3] op_sel_hi:[1,0]
	v_cvt_pk_bf16_f32 v8, v8, v9
	v_cvt_pk_bf16_f32 v9, v10, v11
	global_store_dwordx2 v[4:5], v[6:7], off offset:16
	global_store_dwordx2 v[4:5], v[8:9], off offset:80
	v_pk_mul_f32 v[6:7], v[42:43], v[2:3] op_sel_hi:[1,0]
	v_pk_mul_f32 v[8:9], v[44:45], v[2:3] op_sel_hi:[1,0]
	v_cvt_pk_bf16_f32 v6, v6, v7
	v_cvt_pk_bf16_f32 v7, v8, v9
	v_pk_mul_f32 v[8:9], v[58:59], v[2:3] op_sel_hi:[1,0]
	v_pk_mul_f32 v[10:11], v[60:61], v[2:3] op_sel_hi:[1,0]
	v_cvt_pk_bf16_f32 v8, v8, v9
	v_cvt_pk_bf16_f32 v9, v10, v11
	global_store_dwordx2 v[4:5], v[6:7], off offset:32
	global_store_dwordx2 v[4:5], v[8:9], off offset:96
	v_pk_mul_f32 v[6:7], v[46:47], v[2:3] op_sel_hi:[1,0]
	v_pk_mul_f32 v[8:9], v[48:49], v[2:3] op_sel_hi:[1,0]
	v_cvt_pk_bf16_f32 v6, v6, v7
	v_cvt_pk_bf16_f32 v7, v8, v9
	v_pk_mul_f32 v[8:9], v[62:63], v[2:3] op_sel_hi:[1,0]
	v_pk_mul_f32 v[2:3], v[64:65], v[2:3] op_sel_hi:[1,0]
	v_cvt_pk_bf16_f32 v8, v8, v9
	v_cvt_pk_bf16_f32 v9, v2, v3
	global_store_dwordx2 v[4:5], v[6:7], off offset:48
	global_store_dwordx2 v[4:5], v[8:9], off offset:112

; DI unsigned pk_bf16(float lo, float hi) { f32x2 v = {lo, hi}; bf16x2_t b = __builtin_convertvector(v, bf16x2_t); return __builtin_bit_cast(unsigned, b); }
; DI void slc_unit(const Params& P, lptr L, int u, int tid, int lane, int wid) {
;     ...
;     float l = rs.l; l += __shfl_xor(l, 32);
;     const float sc = gs / fmaxf(l, 1e-30f);
;     const float* prow = PART + row * 512 + head * 64;
;     bf16_t* orow = ATT + row * DM + 512 + head * 64;
; #pragma unroll
;     for (int g4 = 0; g4 < 4; ++g4) {
;         const f32x4 a = *(const f32x4*)(prow + 8 * g4 + 4 * hi), c = *(const f32x4*)(prow + 32 + 8 * g4 + 4 * hi);
;         u32x2 w0, w1;
;         w0.x = pk_bf16(a[0] + o0[4 * g4] * sc, a[1] + o0[4 * g4 + 1] * sc); w0.y = pk_bf16(a[2] + o0[4 * g4 + 2] * sc, a[3] + o0[4 * g4 + 3] * sc);
;         w1.x = pk_bf16(c[0] + o1[4 * g4] * sc, c[1] + o1[4 * g4 + 1] * sc); w1.y = pk_bf16(c[2] + o1[4 * g4 + 2] * sc, c[3] + o1[4 * g4 + 3] * sc);
;         *(u32x2*)(orow + 8 * g4 + 4 * hi) = w0; *(u32x2*)(orow + 32 + 8 * g4 + 4 * hi) = w1;
;     }
.LBB0_624:
	v_mov_b32_e32 v91, v1
	v_mov_b32_e32 v155, v1
	s_mov_b32 s61, s83
	v_readlane_b32 s0, v250, 0
	v_readlane_b32 s1, v250, 1
	v_lshlrev_b64 v[62:63], 11, v[90:91]
	s_nop 0
	v_lshl_add_u64 v[62:63], s[0:1], 0, v[62:63]
	v_lshl_add_u64 v[62:63], v[62:63], 0, s[60:61]
	v_lshl_add_u64 v[62:63], v[62:63], 0, v[154:155]
	global_load_dwordx4 v[228:231], v[62:63], off
	global_load_dwordx4 v[232:235], v[62:63], off offset:128
	global_load_dwordx4 v[236:239], v[62:63], off offset:32
	global_load_dwordx4 v[240:243], v[62:63], off offset:160
	global_load_dwordx4 v[244:247], v[62:63], off offset:64
	global_load_dwordx4 v[50:53], v[62:63], off offset:192
	global_load_dwordx4 v[54:57], v[62:63], off offset:96
	global_load_dwordx4 v[58:61], v[62:63], off offset:224
	s_mov_b64 s[0:1], exec
	v_readlane_b32 s2, v251, 20
	v_readlane_b32 s3, v251, 21
	s_and_b64 s[2:3], s[0:1], s[2:3]
	s_mov_b64 exec, s[2:3]
	s_cbranch_execz .Lq_site1_skip
	v_mov_b32_e32 v249, 1
	global_atomic_add v249, v1, v249, s[34:35] sc0
.Lq_site1_skip:
	s_mov_b64 exec, s[0:1]
	s_mov_b32 s98, 1
	s_cmp_lg_u64 s[2:3], 0
	s_cbranch_scc1 .Lq_w0epi
	v_lshlrev_b32_e32 v0, 16, v98
	v_mul_f32_e32 v0, 0xbfb8aa3b, v0
	v_exp_f32_e32 v0, v0
	v_mov_b32_e32 v91, v1
	s_mov_b32 s61, s83
	v_mov_b32_e32 v155, v1
	v_add_f32_e32 v0, 1.0, v0
	v_div_scale_f32 v34, s[0:1], v0, v0, 1.0
	v_rcp_f32_e32 v35, v34
	s_nop 0
	v_fma_f32 v36, -v34, v35, 1.0
	v_fmac_f32_e32 v35, v36, v35
	v_div_scale_f32 v36, vcc, 1.0, v0, 1.0
	v_mul_f32_e32 v37, v36, v35
	v_fma_f32 v38, -v34, v37, v36
	v_fmac_f32_e32 v37, v38, v35
	v_fma_f32 v34, -v34, v37, v36
	v_div_fmas_f32 v34, v34, v35, v37
	v_div_fixup_f32 v0, v34, v0, 1.0
	ds_bpermute_b32 v34, v149, v100
	s_waitcnt lgkmcnt(0)
	v_add_f32_e32 v34, v100, v34
	v_max_f32_e32 v34, 0xda24260, v34
	v_div_scale_f32 v35, s[0:1], v34, v34, v0
	v_rcp_f32_e32 v36, v35
	v_readlane_b32 s0, v250, 0
	v_readlane_b32 s1, v250, 1
	v_fma_f32 v37, -v35, v36, 1.0
	v_fmac_f32_e32 v36, v37, v36
	v_div_scale_f32 v37, vcc, v0, v34, v0
	v_mul_f32_e32 v38, v37, v36
	v_fma_f32 v39, -v35, v38, v37
	v_fmac_f32_e32 v38, v39, v36
	v_fma_f32 v35, -v35, v38, v37
	v_div_fmas_f32 v35, v35, v36, v38
	v_lshlrev_b64 v[36:37], 11, v[90:91]
	v_lshl_add_u64 v[38:39], s[0:1], 0, v[36:37]
	v_lshl_add_u64 v[38:39], v[38:39], 0, s[60:61]
	v_lshl_add_u64 v[46:47], v[38:39], 0, v[154:155]
	v_lshl_add_u64 v[36:37], s[34:35], 0, v[36:37]
	v_div_fixup_f32 v34, v35, v34, v0
	v_lshl_add_u64 v[36:37], v[36:37], 0, s[82:83]
	v_lshlrev_b32_e32 v0, 1, v134
	v_lshl_add_u64 v[48:49], v[36:37], 0, v[0:1]
	s_mov_b64 s[0:1], 0x3800400
	v_lshl_add_u64 v[36:37], v[48:49], 0, s[0:1]
	s_mov_b32 s0, 0x3800000
	s_waitcnt vmcnt(7)
	v_pk_fma_f32 v[18:19], v[18:19], v[34:35], v[228:229] op_sel_hi:[1,0,1]
	s_waitcnt vmcnt(6)
	v_pk_fma_f32 v[2:3], v[2:3], v[34:35], v[232:233] op_sel_hi:[1,0,1]
	v_pk_fma_f32 v[4:5], v[4:5], v[34:35], v[234:235] op_sel_hi:[1,0,1]
	v_pk_fma_f32 v[20:21], v[20:21], v[34:35], v[230:231] op_sel_hi:[1,0,1]
	v_cvt_pk_bf16_f32 v2, v2, v3
	v_cvt_pk_bf16_f32 v3, v4, v5
	v_add_co_u32_e32 v4, vcc, s0, v48
	v_cvt_pk_bf16_f32 v18, v18, v19
	v_cvt_pk_bf16_f32 v19, v20, v21
	v_addc_co_u32_e32 v5, vcc, 0, v49, vcc
	global_store_dwordx2 v[4:5], v[18:19], off offset:1024
	global_store_dwordx2 v[36:37], v[2:3], off offset:64
	s_nop 0
	s_mov_b64 s[0:1], -1
	s_waitcnt vmcnt(7)
	v_pk_fma_f32 v[2:3], v[22:23], v[34:35], v[236:237] op_sel_hi:[1,0,1]
	v_pk_fma_f32 v[4:5], v[24:25], v[34:35], v[238:239] op_sel_hi:[1,0,1]
	v_cvt_pk_bf16_f32 v2, v2, v3
	v_cvt_pk_bf16_f32 v3, v4, v5
	s_waitcnt vmcnt(6)
	v_pk_fma_f32 v[4:5], v[6:7], v[34:35], v[240:241] op_sel_hi:[1,0,1]
	v_pk_fma_f32 v[6:7], v[8:9], v[34:35], v[242:243] op_sel_hi:[1,0,1]
	v_cvt_pk_bf16_f32 v4, v4, v5
	v_cvt_pk_bf16_f32 v5, v6, v7
	global_store_dwordx2 v[36:37], v[2:3], off offset:16
	global_store_dwordx2 v[36:37], v[4:5], off offset:80
	s_nop 0
	s_waitcnt vmcnt(7)
	v_pk_fma_f32 v[2:3], v[26:27], v[34:35], v[244:245] op_sel_hi:[1,0,1]
	v_pk_fma_f32 v[4:5], v[28:29], v[34:35], v[246:247] op_sel_hi:[1,0,1]
	v_cvt_pk_bf16_f32 v2, v2, v3
	v_cvt_pk_bf16_f32 v3, v4, v5
	s_waitcnt vmcnt(6)
	v_pk_fma_f32 v[4:5], v[10:11], v[34:35], v[50:51] op_sel_hi:[1,0,1]
	v_pk_fma_f32 v[6:7], v[12:13], v[34:35], v[52:53] op_sel_hi:[1,0,1]
	v_cvt_pk_bf16_f32 v4, v4, v5
	v_cvt_pk_bf16_f32 v5, v6, v7
	global_store_dwordx2 v[36:37], v[2:3], off offset:32
	global_store_dwordx2 v[36:37], v[4:5], off offset:96
	s_nop 0
	s_waitcnt vmcnt(7)
	v_pk_fma_f32 v[6:7], v[30:31], v[34:35], v[54:55] op_sel_hi:[1,0,1]
	v_pk_fma_f32 v[8:9], v[32:33], v[34:35], v[56:57] op_sel_hi:[1,0,1]
	v_cvt_pk_bf16_f32 v6, v6, v7
	v_cvt_pk_bf16_f32 v7, v8, v9
	s_waitcnt vmcnt(6)
	v_pk_fma_f32 v[2:3], v[14:15], v[34:35], v[58:59] op_sel_hi:[1,0,1]
	v_pk_fma_f32 v[4:5], v[16:17], v[34:35], v[60:61] op_sel_hi:[1,0,1]
	v_cvt_pk_bf16_f32 v2, v2, v3
	v_cvt_pk_bf16_f32 v3, v4, v5
	global_store_dwordx2 v[36:37], v[6:7], off offset:48
	global_store_dwordx2 v[36:37], v[2:3], off offset:112
	s_branch .LBB0_625
; DI unsigned pk_bf16(float lo, float hi) { f32x2 v = {lo, hi}; bf16x2_t b = __builtin_convertvector(v, bf16x2_t); return __builtin_bit_cast(unsigned, b); }
; DI void slc_unit(const Params& P, lptr L, int u, int tid, int lane, int wid) {
;     ...
;     float l = rs.l; l += __shfl_xor(l, 32);
;     const float sc = gs / fmaxf(l, 1e-30f);
;     const float* prow = PART + row * 512 + head * 64;
;     bf16_t* orow = ATT + row * DM + 512 + head * 64;
; #pragma unroll
;     for (int g4 = 0; g4 < 4; ++g4) {
;         const f32x4 a = *(const f32x4*)(prow + 8 * g4 + 4 * hi), c = *(const f32x4*)(prow + 32 + 8 * g4 + 4 * hi);
;         u32x2 w0, w1;
;         w0.x = pk_bf16(a[0] + o0[4 * g4] * sc, a[1] + o0[4 * g4 + 1] * sc); w0.y = pk_bf16(a[2] + o0[4 * g4 + 2] * sc, a[3] + o0[4 * g4 + 3] * sc);
;         w1.x = pk_bf16(c[0] + o1[4 * g4] * sc, c[1] + o1[4 * g4 + 1] * sc); w1.y = pk_bf16(c[2] + o1[4 * g4 + 2] * sc, c[3] + o1[4 * g4 + 3] * sc);
;         *(u32x2*)(orow + 8 * g4 + 4 * hi) = w0; *(u32x2*)(orow + 32 + 8 * g4 + 4 * hi) = w1;
;     }
.Lq_w0epi:
	v_lshlrev_b32_e32 v0, 16, v98
	v_mul_f32_e32 v0, 0xbfb8aa3b, v0
	v_exp_f32_e32 v0, v0
	v_mov_b32_e32 v91, v1
	s_mov_b32 s61, s83
	v_mov_b32_e32 v155, v1
	v_add_f32_e32 v0, 1.0, v0
	v_div_scale_f32 v34, s[0:1], v0, v0, 1.0
	v_rcp_f32_e32 v35, v34
	s_nop 0
	v_fma_f32 v36, -v34, v35, 1.0
	v_fmac_f32_e32 v35, v36, v35
	v_div_scale_f32 v36, vcc, 1.0, v0, 1.0
	v_mul_f32_e32 v37, v36, v35
	v_fma_f32 v38, -v34, v37, v36
	v_fmac_f32_e32 v37, v38, v35
	v_fma_f32 v34, -v34, v37, v36
	v_div_fmas_f32 v34, v34, v35, v37
	v_div_fixup_f32 v0, v34, v0, 1.0
	ds_bpermute_b32 v34, v149, v100
	s_waitcnt lgkmcnt(0)
	v_add_f32_e32 v34, v100, v34
	v_max_f32_e32 v34, 0xda24260, v34
	v_div_scale_f32 v35, s[0:1], v34, v34, v0
	v_rcp_f32_e32 v36, v35
	v_readlane_b32 s0, v250, 0
	v_readlane_b32 s1, v250, 1
	v_fma_f32 v37, -v35, v36, 1.0
	v_fmac_f32_e32 v36, v37, v36
	v_div_scale_f32 v37, vcc, v0, v34, v0
	v_mul_f32_e32 v38, v37, v36
	v_fma_f32 v39, -v35, v38, v37
	v_fmac_f32_e32 v38, v39, v36
	v_fma_f32 v35, -v35, v38, v37
	v_div_fmas_f32 v35, v35, v36, v38
	v_lshlrev_b64 v[36:37], 11, v[90:91]
	v_lshl_add_u64 v[38:39], s[0:1], 0, v[36:37]
	v_lshl_add_u64 v[38:39], v[38:39], 0, s[60:61]
	v_lshl_add_u64 v[46:47], v[38:39], 0, v[154:155]
	v_lshl_add_u64 v[36:37], s[34:35], 0, v[36:37]
	v_div_fixup_f32 v34, v35, v34, v0
	v_lshl_add_u64 v[36:37], v[36:37], 0, s[82:83]
	v_lshlrev_b32_e32 v0, 1, v134
	v_lshl_add_u64 v[48:49], v[36:37], 0, v[0:1]
	s_mov_b64 s[0:1], 0x3800400
	v_lshl_add_u64 v[36:37], v[48:49], 0, s[0:1]
	s_mov_b32 s0, 0x3800000
	s_waitcnt vmcnt(8)
	v_pk_fma_f32 v[18:19], v[18:19], v[34:35], v[228:229] op_sel_hi:[1,0,1]
	s_waitcnt vmcnt(7)
	v_pk_fma_f32 v[2:3], v[2:3], v[34:35], v[232:233] op_sel_hi:[1,0,1]
	v_pk_fma_f32 v[4:5], v[4:5], v[34:35], v[234:235] op_sel_hi:[1,0,1]
	v_pk_fma_f32 v[20:21], v[20:21], v[34:35], v[230:231] op_sel_hi:[1,0,1]
	v_cvt_pk_bf16_f32 v2, v2, v3
	v_cvt_pk_bf16_f32 v3, v4, v5
	v_add_co_u32_e32 v4, vcc, s0, v48
	v_cvt_pk_bf16_f32 v18, v18, v19
	v_cvt_pk_bf16_f32 v19, v20, v21
	v_addc_co_u32_e32 v5, vcc, 0, v49, vcc
	global_store_dwordx2 v[4:5], v[18:19], off offset:1024
	global_store_dwordx2 v[36:37], v[2:3], off offset:64
	s_nop 0
	s_mov_b64 s[0:1], -1
	s_waitcnt vmcnt(8)
	v_pk_fma_f32 v[2:3], v[22:23], v[34:35], v[236:237] op_sel_hi:[1,0,1]
	v_pk_fma_f32 v[4:5], v[24:25], v[34:35], v[238:239] op_sel_hi:[1,0,1]
	v_cvt_pk_bf16_f32 v2, v2, v3
	v_cvt_pk_bf16_f32 v3, v4, v5
	s_waitcnt vmcnt(7)
	v_pk_fma_f32 v[4:5], v[6:7], v[34:35], v[240:241] op_sel_hi:[1,0,1]
	v_pk_fma_f32 v[6:7], v[8:9], v[34:35], v[242:243] op_sel_hi:[1,0,1]
	v_cvt_pk_bf16_f32 v4, v4, v5
	v_cvt_pk_bf16_f32 v5, v6, v7
	global_store_dwordx2 v[36:37], v[2:3], off offset:16
	global_store_dwordx2 v[36:37], v[4:5], off offset:80
	s_nop 0
	s_waitcnt vmcnt(8)
	v_pk_fma_f32 v[2:3], v[26:27], v[34:35], v[244:245] op_sel_hi:[1,0,1]
	v_pk_fma_f32 v[4:5], v[28:29], v[34:35], v[246:247] op_sel_hi:[1,0,1]
	v_cvt_pk_bf16_f32 v2, v2, v3
	v_cvt_pk_bf16_f32 v3, v4, v5
	s_waitcnt vmcnt(7)
	v_pk_fma_f32 v[4:5], v[10:11], v[34:35], v[50:51] op_sel_hi:[1,0,1]
	v_pk_fma_f32 v[6:7], v[12:13], v[34:35], v[52:53] op_sel_hi:[1,0,1]
	v_cvt_pk_bf16_f32 v4, v4, v5
	v_cvt_pk_bf16_f32 v5, v6, v7
	global_store_dwordx2 v[36:37], v[2:3], off offset:32
	global_store_dwordx2 v[36:37], v[4:5], off offset:96
	s_nop 0
	s_waitcnt vmcnt(8)
	v_pk_fma_f32 v[6:7], v[30:31], v[34:35], v[54:55] op_sel_hi:[1,0,1]
	v_pk_fma_f32 v[8:9], v[32:33], v[34:35], v[56:57] op_sel_hi:[1,0,1]
	v_cvt_pk_bf16_f32 v6, v6, v7
	v_cvt_pk_bf16_f32 v7, v8, v9
	s_waitcnt vmcnt(7)
	v_pk_fma_f32 v[2:3], v[14:15], v[34:35], v[58:59] op_sel_hi:[1,0,1]
	v_pk_fma_f32 v[4:5], v[16:17], v[34:35], v[60:61] op_sel_hi:[1,0,1]
	v_cvt_pk_bf16_f32 v2, v2, v3
	v_cvt_pk_bf16_f32 v3, v4, v5
	global_store_dwordx2 v[36:37], v[6:7], off offset:48
	global_store_dwordx2 v[36:37], v[2:3], off offset:112
